# G1 epilogue: wave owns 128 contiguous bytes per row (B-tile staging column remap), DPP half-row exchange, stores cover 8 rows x 128B instead of 16 rows x 64B
# speedup vs baseline: 1.0155x; 1.0155x over previous
; #define PG8_STAGE(bufoff, gbase, voff) do { _Pragma("unroll") for (int _i = 0; _i < 2; ++_i) \
;         __builtin_amdgcn_global_load_lds((const unsigned*)((const char*)(gbase) + (voff)[_i]), (PG8_LAS unsigned*)(lds + (bufoff) + ldsw + _i * 8192), 16, 0, 0); } while (0)
; #define PG8_WAIT_V(n) asm volatile("s_waitcnt vmcnt(" #n ")" ::: "memory")
; #define PG8_BAR __builtin_amdgcn_s_barrier()
; template <class Epi, class Sched, bool ALIGN_EPI = false, bool SP2 = false>
; __device__ __forceinline__ void gemm_phase(PG8_LAS unsigned char* lds, const Gemm g, const Sched& S, const Epi& E) {
;     ...
;     for (int i = 0; i < 2; ++i) { int R, C; stage_rc(tid * 16 + i * 8192, R, C); const int Rb = Epi::PERM ? ((R & ~31) + perm32(R & 31)) : R;
;         voffA[i] = (unsigned)(R * K + C) * 2u; voffB[i] = (unsigned)(Rb * K + C) * 2u; }
;     const size_t kstep = (size_t)(BK * 2);
;     const size_t hstep = (size_t)HALF * K * 2;
;     const size_t tstep = 2 * hstep;
;     const unsigned ldsw = (unsigned)wid * 1024u;
;     const int aoff = lds_byte(wr * 64 + fr, fq * 8), boff = lds_byte(wc * 32 + fr, fq * 8);
;     ...
;     Unit cur, nxt; int ui = 0;
;     if (!S.next(0, cur)) return;
;     f32x4 acc[2][2][4][2];
; #pragma unroll
;     for (int a = 0; a < 2; ++a)
; #pragma unroll
;         for (int b = 0; b < 2; ++b)
; #pragma unroll
;             for (int m = 0; m < 4; ++m)
; #pragma unroll
;                 for (int n = 0; n < 2; ++n) acc[a][b][m][n] = (f32x4){0.f, 0.f, 0.f, 0.f};
;     bf16x8 At[4][2], B0[2][2], B1[2][2];
;     const char* cA = (const char*)g.A + (size_t)cur.pm * tstep; const char* cB = (const char*)g.Bt + (size_t)cur.pn * tstep;
;     S.a_ready(cur);
;     if constexpr (SP2) {
;         PG8_STAGE(PG8_SB(0, 0), cB, voffB); PG8_STAGE(PG8_SB(0, 1), cB + hstep, voffB); PG8_STAGE(PG8_SA(0, 0), cA, voffA); PG8_STAGE(PG8_SA(0, 1), cA + hstep, voffA);
;         if (wr == 1) PG8_BAR;
;         PG8_WAIT_V(2); PG8_BAR;
;         PG8_STAGE(PG8_SB(1, 0), cB + kstep, voffB); PG8_STAGE(PG8_SA(1, 0), cA + kstep, voffA); PG8_STAGE(PG8_SB(1, 1), cB + hstep + kstep, voffB);
;         PG8_WAIT_V(6); PG8_BAR;
.LBB0_146:
	s_mov_b32 s0, s2
	v_writelane_b32 v254, s0, 52
	s_lshl_b32 s2, s2, 15
	v_mov_b32_e32 v0, v188
	v_writelane_b32 v254, s1, 53
	s_nop 0
	v_readlane_b32 s0, v254, 6
	v_readlane_b32 s1, v254, 7
	s_mov_b32 s3, s1
	s_lshl_b64 s[4:5], s[2:3], 11
	v_readlane_b32 s0, v251, 52
	s_add_u32 s26, s0, s4
	v_writelane_b32 v254, s4, 54
	v_readlane_b32 s0, v251, 53
	s_addc_u32 s27, s0, s5
	v_writelane_b32 v254, s5, 55
	v_writelane_b32 v254, s2, 56
	s_lshl_b64 s[0:1], s[2:3], 6
	s_nop 0
	v_writelane_b32 v254, s3, 57
	v_readlane_b32 s2, v251, 50
	s_add_u32 s8, s2, s0
	v_readlane_b32 s2, v251, 54
	v_readlane_b32 s0, v251, 51
	v_readlane_b32 s3, v251, 55
	s_addc_u32 s9, s0, s1
	v_readfirstlane_b32 s0, v0
	s_and_b64 vcc, exec, s[2:3]
	s_cbranch_vccz .LBB0_216
	v_lshlrev_b32_e32 v2, 4, v0
	v_add_u32_e32 v3, 0x2000, v2
	v_ashrrev_i32_e32 v4, 31, v3
	v_lshrrev_b32_e32 v4, 22, v4
	v_add_u32_e32 v4, v3, v4
	v_ashrrev_i32_e32 v6, 10, v4
	v_mul_i32_i24_e32 v4, 0x400, v6
	v_sub_u32_e32 v3, v3, v4
	v_lshrrev_b32_e32 v4, 4, v3
	v_bitop3_b32 v3, v4, v3, 32 bitop3:0x6c
	v_ashrrev_i32_e32 v4, 31, v3
	v_lshrrev_b32_e32 v4, 26, v4
	v_add_u32_e32 v4, v3, v4
	v_lshlrev_b32_e32 v5, 3, v6
	v_ashrrev_i32_e32 v7, 6, v4
	v_and_b32_e32 v5, -16, v5
	v_add_u32_e32 v5, v7, v5
	v_and_b32_e32 v8, 3, v7
	s_mov_b32 s2, 0x1fffe0
	v_lshrrev_b32_e32 v9, 2, v5
	v_lshlrev_b32_e32 v10, 1, v5
	v_and_b32_e32 v4, 0xc0, v4
	v_and_or_b32 v8, v5, s2, v8
	v_and_b32_e32 v9, 4, v9
	v_and_b32_e32 v10, 24, v10
	v_sub_u32_e32 v3, v3, v4
	v_or3_b32 v9, v8, v9, v10
	v_lshlrev_b32_e32 v8, 5, v6
	v_ashrrev_i16_sdwa v3, v189, sext(v3) dst_sel:DWORD dst_unused:UNUSED_PAD src0_sel:DWORD src1_sel:BYTE_0
	v_and_b32_e32 v10, 32, v8
	v_bfe_i32 v8, v3, 0, 16
	v_add_lshl_u32 v3, v10, v8, 1
	v_lshl_add_u32 v146, v9, 11, v3
	v_lshl_add_u32 v148, v5, 11, v3
	v_bfe_i32 v3, v0, 27, 1
	v_lshrrev_b32_e32 v3, 22, v3
	v_add_u32_e32 v3, v2, v3
	v_and_b32_e32 v3, 0xfffffc00, v3
	v_sub_u32_e32 v2, v2, v3
	v_lshrrev_b32_e32 v3, 4, v2
	v_ashrrev_i32_e32 v4, 31, v0
	v_bitop3_b32 v2, v3, v2, 32 bitop3:0x6c
	v_lshrrev_b32_e32 v4, 26, v4
	v_ashrrev_i32_e32 v3, 31, v2
	v_add_u32_e32 v4, v0, v4
	v_lshrrev_b32_e32 v3, 26, v3
	v_ashrrev_i32_e32 v10, 6, v4
	v_add_u32_e32 v3, v2, v3
	v_lshlrev_b32_e32 v4, 3, v10
	v_ashrrev_i32_e32 v9, 6, v3
	v_and_b32_e32 v4, -16, v4
	v_add_u32_e32 v4, v9, v4
	v_and_b32_e32 v5, 3, v9
	v_lshrrev_b32_e32 v11, 2, v4
	v_lshlrev_b32_e32 v12, 1, v4
	v_and_b32_e32 v3, 0xc0, v3
	v_and_or_b32 v5, v4, s2, v5
	v_and_b32_e32 v11, 4, v11
	v_and_b32_e32 v12, 24, v12
	v_sub_u32_e32 v2, v2, v3
	s_ashr_i32 s4, s0, 6
	v_or3_b32 v5, v5, v11, v12
	v_lshlrev_b32_e32 v11, 5, v10
	v_ashrrev_i16_sdwa v2, v189, sext(v2) dst_sel:DWORD dst_unused:UNUSED_PAD src0_sel:DWORD src1_sel:BYTE_0
	s_lshl_b32 s28, s4, 10
	v_and_b32_e32 v12, 32, v11
	v_bfe_i32 v11, v2, 0, 16
	v_add_lshl_u32 v2, v12, v11, 1
	s_add_i32 s29, s28, 0
	v_readlane_b32 s2, v253, 28
	v_lshl_add_u32 v150, v5, 11, v2
	s_add_i32 m0, s29, 0x10000
	v_readlane_b32 s3, v253, 29
	s_ashr_i32 s1, s0, 8
	s_lshl_b32 s98, s1, 16
	v_add_u32_e32 v150, s98, v150
	s_add_i32 s99, s98, 0x20000
	v_add_u32_e32 v146, s99, v146
	v_lshl_add_u32 v152, v4, 11, v2
	v_mov_b32_e32 v153, v1
	v_mov_b32_e32 v149, v1
	s_nop 0
	global_load_lds_dwordx4 v150, s[2:3]
	s_add_i32 m0, s29, 0x12000
	s_nop 0
	global_load_lds_dwordx4 v146, s[2:3]
	v_readlane_b32 s2, v253, 26
	s_add_i32 m0, s29, 0x14000
	v_readlane_b32 s3, v253, 27
	s_nop 4
	s_sub_u32 s2, s2, 0x30000
	s_subb_u32 s3, s3, 0
	s_nop 0
	global_load_lds_dwordx4 v150, s[2:3]
	s_add_i32 m0, s29, 0x16000
	s_nop 0
	global_load_lds_dwordx4 v146, s[2:3]
	v_readlane_b32 s2, v253, 24
	v_readlane_b32 s3, v253, 25
	s_add_u32 s2, s26, s2
	s_addc_u32 s3, s27, s3
	s_add_i32 s30, s29, 0x2000
	s_mov_b32 m0, s29
	s_add_u32 s6, s2, 0x40000
	global_load_lds_dwordx4 v152, s[2:3]
	s_mov_b32 m0, s30
	s_addc_u32 s7, s3, 0
	s_add_i32 s31, s29, 0x4000
	global_load_lds_dwordx4 v148, s[2:3]
	s_mov_b32 m0, s31
	s_add_i32 s34, s29, 0x6000
	global_load_lds_dwordx4 v152, s[6:7]
	s_mov_b32 m0, s34
	s_cmp_eq_u32 s1, 1
	global_load_lds_dwordx4 v148, s[6:7]
	v_lshl_add_u64 v[2:3], s[2:3], 0, v[152:153]
	s_cselect_b64 s[10:11], -1, 0
	s_cmp_lg_u32 s1, 1
	v_lshl_add_u64 v[4:5], s[2:3], 0, v[148:149]
	s_cbranch_scc1 .LBB0_149
	s_barrier
.LBB0_149:
	v_readlane_b32 s6, v253, 28
	v_mov_b32_e32 v151, v1
	v_readlane_b32 s7, v253, 29
	v_mov_b32_e32 v147, v1
	s_add_i32 m0, s29, 0x18000
	v_lshl_add_u64 v[12:13], s[6:7], 0, v[150:151]
	v_lshl_add_u64 v[14:15], s[6:7], 0, v[146:147]
	v_lshl_add_u64 v[12:13], v[12:13], 0, s[84:85]
	s_waitcnt vmcnt(2)
	s_barrier
	global_load_lds_dwordx4 v[12:13], off
	v_lshl_add_u64 v[12:13], v[14:15], 0, s[84:85]
	s_add_i32 m0, s29, 0x1a000
	s_add_i32 s35, s29, 0x8000
	global_load_lds_dwordx4 v[12:13], off
	v_lshl_add_u64 v[2:3], v[2:3], 0, s[84:85]
	s_mov_b32 m0, s35
	s_add_i32 s36, s29, 0xa000
	v_readlane_b32 s12, v253, 30
	global_load_lds_dwordx4 v[2:3], off
	v_lshl_add_u64 v[2:3], v[4:5], 0, s[84:85]
	s_mov_b32 m0, s36
	v_readlane_b32 s13, v253, 31
	global_load_lds_dwordx4 v[2:3], off
	s_add_i32 m0, s29, 0x1c000
	s_sub_u32 s12, s12, 0x30000
	s_subb_u32 s13, s13, 0
	v_lshl_add_u64 v[2:3], s[12:13], 0, v[150:151]
	global_load_lds_dwordx4 v[2:3], off
	v_lshl_add_u64 v[2:3], s[12:13], 0, v[146:147]
	s_add_i32 m0, s29, 0x1e000
	s_and_b32 s4, s4, 3
	global_load_lds_dwordx4 v[2:3], off
	v_bfe_u32 v3, v0, 4, 2
	v_and_b32_e32 v2, 15, v0
	v_lshlrev_b32_e32 v5, 4, v3
	v_lshlrev_b32_e32 v0, 2, v0
	v_lshl_or_b32 v155, s1, 6, v2
	v_lshl_or_b32 v2, v2, 6, v5
	s_lshl_b32 s1, s1, 13
	v_and_b32_e32 v0, 32, v0
	v_bitop3_b32 v5, v2, s1, v0 bitop3:0xde
	s_lshl_b32 s1, s4, 12
	v_bitop3_b32 v199, v2, s1, v0 bitop3:0xde
	v_lshlrev_b32_e32 v0, 5, v3
	v_lshl_add_u64 v[156:157], s[8:9], 0, v[0:1]
	v_lshl_add_u64 v[158:159], s[66:67], 0, v[0:1]
	v_lshlrev_b32_e32 v0, 14, v10
	v_and_b32_e32 v0, 0xffff8000, v0
	v_lshl_add_u32 v0, v9, 11, v0
	v_and_b32_e32 v2, 1, v10
	v_lshl_or_b32 v0, v2, 6, v0
	v_lshl_add_u32 v160, v11, 1, v0
	v_lshlrev_b32_e32 v0, 14, v6
	v_lshlrev_b32_e32 v4, 3, v3
	s_cmpk_lt_u32 s0, 0x100
	v_and_b32_e32 v0, 0xffff8000, v0
	s_waitcnt vmcnt(6)
	s_cselect_b64 s[12:13], -1, 0
	s_cmp_eq_u32 s4, 0
	v_lshl_or_b32 v154, s4, 5, v4
	v_lshl_add_u32 v0, v7, 11, v0
	v_and_b32_e32 v2, 1, v6
	v_readlane_b32 s4, v252, 36
	s_cselect_b64 s[0:1], -1, 0
	v_cmp_gt_u32_e32 vcc, 2, v3
	v_lshl_or_b32 v0, v2, 6, v0
	s_mov_b32 s64, s4
	v_readlane_b32 s4, v253, 22
	v_readlane_b32 s48, v251, 32
	s_mov_b32 s37, 0
	s_and_b64 s[14:15], s[0:1], vcc
	v_cmp_eq_u32_e64 s[0:1], 1, v3
	v_mov_b32_e32 v161, v1
	v_lshl_add_u32 v178, v8, 1, v0
	v_mov_b32_e32 v179, v1
	v_add_u32_e32 v200, 0, v5
	s_mov_b32 s33, s4
	v_readlane_b32 s49, v251, 33
	s_movk_i32 s47, 0x261
	s_mov_b32 s52, 0x3f317217
	s_mov_b32 s53, 0x7f800000
	s_barrier
	v_readlane_b32 s5, v253, 23
	s_branch .LBB0_152

; #define PG8_STAGE(bufoff, gbase, voff) do { _Pragma("unroll") for (int _i = 0; _i < 2; ++_i) \
;         __builtin_amdgcn_global_load_lds((const unsigned*)((const char*)(gbase) + (voff)[_i]), (PG8_LAS unsigned*)(lds + (bufoff) + ldsw + _i * 8192), 16, 0, 0); } while (0)
; #define PG8_LDA(dst, b, h) do { _Pragma("unroll") for (int m = 0; m < 4; ++m) _Pragma("unroll") for (int k = 0; k < 2; ++k) dst[m][k] = *(const PG8_LAS bf16x8*)(lds + PG8_SA(b, h) + aoff + m * 2048 + k * 1024); } while (0)
; #define PG8_LDB(dst, b, h) do { _Pragma("unroll") for (int n = 0; n < 2; ++n) _Pragma("unroll") for (int k = 0; k < 2; ++k) dst[n][k] = *(const PG8_LAS bf16x8*)(lds + PG8_SB(b, h) + boff + n * 2048 + k * 1024); } while (0)
; #define PG8_MMA(ai, bj, At, Bt) do { __builtin_amdgcn_s_setprio(1); _Pragma("unroll") for (int m = 0; m < 4; ++m) _Pragma("unroll") for (int n = 0; n < 2; ++n) _Pragma("unroll") for (int k = 0; k < 2; ++k) \
;         acc[ai][bj][m][n] = __builtin_amdgcn_mfma_f32_16x16x32_bf16(Bt[n][k], At[m][k], acc[ai][bj][m][n], 0, 0, 0); __builtin_amdgcn_s_setprio(0); } while (0)
; #define PG8_WAIT_V(n) asm volatile("s_waitcnt vmcnt(" #n ")" ::: "memory")
; #define PG8_WAIT_L(n) asm volatile("s_waitcnt lgkmcnt(" #n ")" ::: "memory")
; #define PG8_BAR __builtin_amdgcn_s_barrier()
; #define PG8_SCHED __builtin_amdgcn_sched_barrier(0)
; template <class Epi, class Sched, bool ALIGN_EPI = false, bool SP2 = false>
; __device__ __forceinline__ void gemm_phase(PG8_LAS unsigned char* lds, const Gemm g, const Sched& S, const Epi& E) {
;     ...
;             PG8_LDB(B0, 0, 0); PG8_LDB(B1, 0, 1); PG8_SCHED; PG8_LDA(At, 0, 0); PG8_STAGE(PG8_SA(1, 1), a1 + hstep, voffA);
;             PG8_WAIT_V(8); PG8_WAIT_L(0); PG8_BAR; PG8_MMA(0, 0, At, B0); PG8_MMA(0, 1, At, B1); PG8_BAR; PG8_SCHED;
;             PG8_LDA(At, 0, 1); PG8_STAGE(PG8_SB(0, 0), b2, voffB); PG8_STAGE(PG8_SB(0, 1), b2 + hstep, voffB); PG8_STAGE(PG8_SA(0, 0), a2, voffA);
;             PG8_WAIT_V(8); PG8_WAIT_L(0); PG8_BAR; PG8_MMA(1, 0, At, B0); PG8_MMA(1, 1, At, B1); PG8_BAR; PG8_SCHED;
.LBB0_155:
	s_add_u32 s6, s2, 0xfffc0080
	s_addc_u32 s7, s3, -1
	s_add_i32 s43, 0, 0x10000
	s_cmp_eq_u32 s42, 12
	s_cselect_b32 s25, s19, s7
	s_cselect_b32 s24, s38, s6
	v_add_u32_e32 v0, s43, v199
	s_cselect_b32 s7, s17, s41
	s_cselect_b32 s6, s39, s40
	s_add_i32 s46, 0, 0x14000
	ds_read_b128 v[130:133], v0
	ds_read_b128 v[134:137], v0 offset:1024
	ds_read_b128 v[138:141], v0 offset:2048
	ds_read_b128 v[142:145], v0 offset:3072
	v_add_u32_e32 v0, s46, v199
	ds_read_b128 v[180:183], v0
	ds_read_b128 v[184:187], v0 offset:1024
	ds_read_b128 v[202:205], v0 offset:2048
	ds_read_b128 v[206:209], v0 offset:3072
	v_lshl_add_u64 v[238:239], s[2:3], 0, v[160:161]
	s_add_i32 m0, s29, 0xc000
	ds_read_b128 v[210:213], v200
	ds_read_b128 v[214:217], v200 offset:1024
	ds_read_b128 v[218:221], v200 offset:2048
	ds_read_b128 v[222:225], v200 offset:3072
	ds_read_b128 v[226:229], v200 offset:4096
	ds_read_b128 v[230:233], v200 offset:5120
	ds_read_b128 v[234:237], v200 offset:6144
	ds_read_b128 v[244:247], v200 offset:7168
	global_load_lds_dwordx4 v[238:239], off
	v_lshl_add_u64 v[238:239], s[2:3], 0, v[178:179]
	s_add_i32 m0, s29, 0xe000
	s_nop 0
	global_load_lds_dwordx4 v[238:239], off
	s_waitcnt vmcnt(8)
	s_waitcnt lgkmcnt(0)
	s_barrier
	s_setprio 1
	s_waitcnt lgkmcnt(0)
	v_mfma_f32_16x16x32_bf16 v[126:129], v[130:133], v[210:213], v[126:129]
	v_mfma_f32_16x16x32_bf16 v[122:125], v[138:141], v[210:213], v[122:125]
	v_mfma_f32_16x16x32_bf16 v[110:113], v[130:133], v[218:221], v[110:113]
	v_mfma_f32_16x16x32_bf16 v[106:109], v[138:141], v[218:221], v[106:109]
	v_mfma_f32_16x16x32_bf16 v[94:97], v[130:133], v[226:229], v[94:97]
	v_mfma_f32_16x16x32_bf16 v[90:93], v[138:141], v[226:229], v[90:93]
	v_mfma_f32_16x16x32_bf16 v[78:81], v[130:133], v[234:237], v[78:81]
	v_mfma_f32_16x16x32_bf16 v[74:77], v[138:141], v[234:237], v[74:77]
	v_mfma_f32_16x16x32_bf16 v[126:129], v[134:137], v[214:217], v[126:129]
	v_mfma_f32_16x16x32_bf16 v[122:125], v[142:145], v[214:217], v[122:125]
	v_mfma_f32_16x16x32_bf16 v[110:113], v[134:137], v[222:225], v[110:113]
	v_mfma_f32_16x16x32_bf16 v[106:109], v[142:145], v[222:225], v[106:109]
	v_mfma_f32_16x16x32_bf16 v[94:97], v[134:137], v[230:233], v[94:97]
	v_mfma_f32_16x16x32_bf16 v[90:93], v[142:145], v[230:233], v[90:93]
	v_mfma_f32_16x16x32_bf16 v[78:81], v[134:137], v[244:247], v[78:81]
	v_mfma_f32_16x16x32_bf16 v[74:77], v[142:145], v[244:247], v[74:77]
	s_setprio 0
	s_setprio 1
	v_mfma_f32_16x16x32_bf16 v[118:121], v[180:183], v[210:213], v[118:121]
	v_mfma_f32_16x16x32_bf16 v[114:117], v[202:205], v[210:213], v[114:117]
	v_mfma_f32_16x16x32_bf16 v[102:105], v[180:183], v[218:221], v[102:105]
	v_mfma_f32_16x16x32_bf16 v[98:101], v[202:205], v[218:221], v[98:101]
	v_mfma_f32_16x16x32_bf16 v[86:89], v[180:183], v[226:229], v[86:89]
	v_mfma_f32_16x16x32_bf16 v[82:85], v[202:205], v[226:229], v[82:85]
	v_mfma_f32_16x16x32_bf16 v[70:73], v[180:183], v[234:237], v[70:73]
	v_mfma_f32_16x16x32_bf16 v[66:69], v[202:205], v[234:237], v[66:69]
	v_mfma_f32_16x16x32_bf16 v[118:121], v[184:187], v[214:217], v[118:121]
	v_mfma_f32_16x16x32_bf16 v[114:117], v[206:209], v[214:217], v[114:117]
	v_mfma_f32_16x16x32_bf16 v[102:105], v[184:187], v[222:225], v[102:105]
	v_mfma_f32_16x16x32_bf16 v[98:101], v[206:209], v[222:225], v[98:101]
	v_mfma_f32_16x16x32_bf16 v[86:89], v[184:187], v[230:233], v[86:89]
	v_mfma_f32_16x16x32_bf16 v[82:85], v[206:209], v[230:233], v[82:85]
	v_mfma_f32_16x16x32_bf16 v[70:73], v[184:187], v[244:247], v[70:73]
	v_mfma_f32_16x16x32_bf16 v[66:69], v[206:209], v[244:247], v[66:69]
	s_setprio 0
	s_barrier
	s_add_i32 s43, s43, s28
	v_lshl_add_u64 v[238:239], s[6:7], 0, v[150:151]
	s_mov_b32 m0, s43
	ds_read_b128 v[210:213], v200 offset:16384
	ds_read_b128 v[214:217], v200 offset:17408
	ds_read_b128 v[218:221], v200 offset:18432
	ds_read_b128 v[222:225], v200 offset:19456
	ds_read_b128 v[226:229], v200 offset:20480
	ds_read_b128 v[230:233], v200 offset:21504
	ds_read_b128 v[234:237], v200 offset:22528
	ds_read_b128 v[244:247], v200 offset:23552
	global_load_lds_dwordx4 v[238:239], off
	s_add_i32 m0, s43, 0x2000
	s_add_u32 s44, s6, 0x10000
	v_lshl_add_u64 v[248:249], s[6:7], 0, v[146:147]
	s_addc_u32 s45, s7, 0
	s_add_i32 s43, s46, s28
	global_load_lds_dwordx4 v[248:249], off
	v_lshl_add_u64 v[190:191], s[44:45], 0, v[150:151]
	s_mov_b32 m0, s43
	v_lshl_add_u64 v[162:163], s[24:25], 0, v[148:149]
	global_load_lds_dwordx4 v[190:191], off
	v_lshl_add_u64 v[190:191], s[44:45], 0, v[146:147]
	s_add_i32 m0, s43, 0x2000
	s_nop 0
	global_load_lds_dwordx4 v[190:191], off
	v_lshl_add_u64 v[190:191], s[24:25], 0, v[152:153]
	s_mov_b32 m0, s29
	s_nop 0
	global_load_lds_dwordx4 v[190:191], off
	s_mov_b32 m0, s30
	s_nop 0
	global_load_lds_dwordx4 v[162:163], off
	s_waitcnt vmcnt(8)
	s_waitcnt lgkmcnt(0)
	s_barrier
; #define PG8_STAGE(bufoff, gbase, voff) do { _Pragma("unroll") for (int _i = 0; _i < 2; ++_i) \
;         __builtin_amdgcn_global_load_lds((const unsigned*)((const char*)(gbase) + (voff)[_i]), (PG8_LAS unsigned*)(lds + (bufoff) + ldsw + _i * 8192), 16, 0, 0); } while (0)
; #define PG8_LDA(dst, b, h) do { _Pragma("unroll") for (int m = 0; m < 4; ++m) _Pragma("unroll") for (int k = 0; k < 2; ++k) dst[m][k] = *(const PG8_LAS bf16x8*)(lds + PG8_SA(b, h) + aoff + m * 2048 + k * 1024); } while (0)
; #define PG8_LDB(dst, b, h) do { _Pragma("unroll") for (int n = 0; n < 2; ++n) _Pragma("unroll") for (int k = 0; k < 2; ++k) dst[n][k] = *(const PG8_LAS bf16x8*)(lds + PG8_SB(b, h) + boff + n * 2048 + k * 1024); } while (0)
; #define PG8_MMA(ai, bj, At, Bt) do { __builtin_amdgcn_s_setprio(1); _Pragma("unroll") for (int m = 0; m < 4; ++m) _Pragma("unroll") for (int n = 0; n < 2; ++n) _Pragma("unroll") for (int k = 0; k < 2; ++k) \
;         acc[ai][bj][m][n] = __builtin_amdgcn_mfma_f32_16x16x32_bf16(Bt[n][k], At[m][k], acc[ai][bj][m][n], 0, 0, 0); __builtin_amdgcn_s_setprio(0); } while (0)
; #define PG8_WAIT_V(n) asm volatile("s_waitcnt vmcnt(" #n ")" ::: "memory")
; #define PG8_WAIT_L(n) asm volatile("s_waitcnt lgkmcnt(" #n ")" ::: "memory")
; #define PG8_BAR __builtin_amdgcn_s_barrier()
; #define PG8_SCHED __builtin_amdgcn_sched_barrier(0)
; template <class Epi, class Sched, bool ALIGN_EPI = false, bool SP2 = false>
; __device__ __forceinline__ void gemm_phase(PG8_LAS unsigned char* lds, const Gemm g, const Sched& S, const Epi& E) {
;     ...
;             PG8_WAIT_V(8); PG8_WAIT_L(0); PG8_BAR; PG8_MMA(1, 0, At, B0); PG8_MMA(1, 1, At, B1); PG8_BAR; PG8_SCHED;
;             PG8_LDB(B0, 1, 0); PG8_LDB(B1, 1, 1); PG8_SCHED; PG8_LDA(At, 1, 0); PG8_STAGE(PG8_SA(0, 1), a2 + hstep, voffA);
;             PG8_WAIT_V(8); PG8_WAIT_L(0); PG8_BAR; PG8_MMA(0, 0, At, B0); PG8_MMA(0, 1, At, B1); PG8_BAR; PG8_SCHED;
;             PG8_LDA(At, 1, 1); PG8_STAGE(PG8_SB(1, 0), b3, voffB); PG8_STAGE(PG8_SB(1, 1), b3 + hstep, voffB); PG8_STAGE(PG8_SA(1, 0), a3, voffA);
	s_setprio 1
	s_waitcnt lgkmcnt(0)
	v_mfma_f32_16x16x32_bf16 v[62:65], v[130:133], v[210:213], v[62:65]
	v_mfma_f32_16x16x32_bf16 v[58:61], v[138:141], v[210:213], v[58:61]
	v_mfma_f32_16x16x32_bf16 v[46:49], v[130:133], v[218:221], v[46:49]
	v_mfma_f32_16x16x32_bf16 v[42:45], v[138:141], v[218:221], v[42:45]
	v_mfma_f32_16x16x32_bf16 v[30:33], v[130:133], v[226:229], v[30:33]
	v_mfma_f32_16x16x32_bf16 v[26:29], v[138:141], v[226:229], v[26:29]
	v_mfma_f32_16x16x32_bf16 v[14:17], v[130:133], v[234:237], v[14:17]
	v_mfma_f32_16x16x32_bf16 v[10:13], v[138:141], v[234:237], v[10:13]
	v_mfma_f32_16x16x32_bf16 v[62:65], v[134:137], v[214:217], v[62:65]
	v_mfma_f32_16x16x32_bf16 v[58:61], v[142:145], v[214:217], v[58:61]
	v_mfma_f32_16x16x32_bf16 v[46:49], v[134:137], v[222:225], v[46:49]
	v_mfma_f32_16x16x32_bf16 v[42:45], v[142:145], v[222:225], v[42:45]
	v_mfma_f32_16x16x32_bf16 v[30:33], v[134:137], v[230:233], v[30:33]
	v_mfma_f32_16x16x32_bf16 v[26:29], v[142:145], v[230:233], v[26:29]
	v_mfma_f32_16x16x32_bf16 v[14:17], v[134:137], v[244:247], v[14:17]
	v_mfma_f32_16x16x32_bf16 v[10:13], v[142:145], v[244:247], v[10:13]
	s_setprio 0
	s_setprio 1
	v_mfma_f32_16x16x32_bf16 v[54:57], v[180:183], v[210:213], v[54:57]
	v_mfma_f32_16x16x32_bf16 v[50:53], v[202:205], v[210:213], v[50:53]
	v_mfma_f32_16x16x32_bf16 v[38:41], v[180:183], v[218:221], v[38:41]
	v_mfma_f32_16x16x32_bf16 v[34:37], v[202:205], v[218:221], v[34:37]
	v_mfma_f32_16x16x32_bf16 v[22:25], v[180:183], v[226:229], v[22:25]
	v_mfma_f32_16x16x32_bf16 v[18:21], v[202:205], v[226:229], v[18:21]
	v_mfma_f32_16x16x32_bf16 v[6:9], v[180:183], v[234:237], v[6:9]
	v_mfma_f32_16x16x32_bf16 v[2:5], v[202:205], v[234:237], v[2:5]
	v_mfma_f32_16x16x32_bf16 v[54:57], v[184:187], v[214:217], v[54:57]
	v_mfma_f32_16x16x32_bf16 v[50:53], v[206:209], v[214:217], v[50:53]
	v_mfma_f32_16x16x32_bf16 v[38:41], v[184:187], v[222:225], v[38:41]
	v_mfma_f32_16x16x32_bf16 v[34:37], v[206:209], v[222:225], v[34:37]
	v_mfma_f32_16x16x32_bf16 v[22:25], v[184:187], v[230:233], v[22:25]
	v_mfma_f32_16x16x32_bf16 v[18:21], v[206:209], v[230:233], v[18:21]
	v_mfma_f32_16x16x32_bf16 v[6:9], v[184:187], v[244:247], v[6:9]
	v_mfma_f32_16x16x32_bf16 v[2:5], v[206:209], v[244:247], v[2:5]
	s_setprio 0
	s_barrier
	s_add_i32 s43, 0, 0x18000
	v_add_u32_e32 v0, s43, v199
	s_add_i32 s44, 0, 0x1c000
	ds_read_b128 v[130:133], v0
	ds_read_b128 v[134:137], v0 offset:1024
	ds_read_b128 v[138:141], v0 offset:2048
	ds_read_b128 v[142:145], v0 offset:3072
	v_add_u32_e32 v0, s44, v199
	ds_read_b128 v[180:183], v0
	ds_read_b128 v[184:187], v0 offset:1024
	ds_read_b128 v[202:205], v0 offset:2048
	ds_read_b128 v[206:209], v0 offset:3072
	s_add_u32 s24, s24, 0x40000
	s_addc_u32 s25, s25, 0
	s_mov_b32 m0, s31
	v_lshl_add_u64 v[164:165], s[24:25], 0, v[152:153]
	ds_read_b128 v[210:213], v200 offset:32768
	ds_read_b128 v[214:217], v200 offset:33792
	ds_read_b128 v[218:221], v200 offset:34816
	ds_read_b128 v[222:225], v200 offset:35840
	ds_read_b128 v[226:229], v200 offset:36864
	ds_read_b128 v[230:233], v200 offset:37888
	ds_read_b128 v[234:237], v200 offset:38912
	ds_read_b128 v[244:247], v200 offset:39936
	global_load_lds_dwordx4 v[164:165], off
	v_lshl_add_u64 v[164:165], s[24:25], 0, v[148:149]
	s_mov_b32 m0, s34
	s_nop 0
	global_load_lds_dwordx4 v[164:165], off
	s_waitcnt vmcnt(8)
	s_waitcnt lgkmcnt(0)
	s_barrier
	s_setprio 1
	s_waitcnt lgkmcnt(0)
	v_mfma_f32_16x16x32_bf16 v[126:129], v[130:133], v[210:213], v[126:129]
	v_mfma_f32_16x16x32_bf16 v[122:125], v[138:141], v[210:213], v[122:125]
	v_mfma_f32_16x16x32_bf16 v[110:113], v[130:133], v[218:221], v[110:113]
	v_mfma_f32_16x16x32_bf16 v[106:109], v[138:141], v[218:221], v[106:109]
	v_mfma_f32_16x16x32_bf16 v[94:97], v[130:133], v[226:229], v[94:97]
	v_mfma_f32_16x16x32_bf16 v[90:93], v[138:141], v[226:229], v[90:93]
	v_mfma_f32_16x16x32_bf16 v[78:81], v[130:133], v[234:237], v[78:81]
	v_mfma_f32_16x16x32_bf16 v[74:77], v[138:141], v[234:237], v[74:77]
	v_mfma_f32_16x16x32_bf16 v[126:129], v[134:137], v[214:217], v[126:129]
	v_mfma_f32_16x16x32_bf16 v[122:125], v[142:145], v[214:217], v[122:125]
	v_mfma_f32_16x16x32_bf16 v[110:113], v[134:137], v[222:225], v[110:113]
	v_mfma_f32_16x16x32_bf16 v[106:109], v[142:145], v[222:225], v[106:109]
	v_mfma_f32_16x16x32_bf16 v[94:97], v[134:137], v[230:233], v[94:97]
	v_mfma_f32_16x16x32_bf16 v[90:93], v[142:145], v[230:233], v[90:93]
	v_mfma_f32_16x16x32_bf16 v[78:81], v[134:137], v[244:247], v[78:81]
	v_mfma_f32_16x16x32_bf16 v[74:77], v[142:145], v[244:247], v[74:77]
	s_setprio 0
	s_setprio 1
	v_mfma_f32_16x16x32_bf16 v[118:121], v[180:183], v[210:213], v[118:121]
	v_mfma_f32_16x16x32_bf16 v[114:117], v[202:205], v[210:213], v[114:117]
	v_mfma_f32_16x16x32_bf16 v[102:105], v[180:183], v[218:221], v[102:105]
	v_mfma_f32_16x16x32_bf16 v[98:101], v[202:205], v[218:221], v[98:101]
	v_mfma_f32_16x16x32_bf16 v[86:89], v[180:183], v[226:229], v[86:89]
	v_mfma_f32_16x16x32_bf16 v[82:85], v[202:205], v[226:229], v[82:85]
	v_mfma_f32_16x16x32_bf16 v[70:73], v[180:183], v[234:237], v[70:73]
	v_mfma_f32_16x16x32_bf16 v[66:69], v[202:205], v[234:237], v[66:69]
	v_mfma_f32_16x16x32_bf16 v[118:121], v[184:187], v[214:217], v[118:121]
	v_mfma_f32_16x16x32_bf16 v[114:117], v[206:209], v[214:217], v[114:117]
	v_mfma_f32_16x16x32_bf16 v[102:105], v[184:187], v[222:225], v[102:105]
	v_mfma_f32_16x16x32_bf16 v[98:101], v[206:209], v[222:225], v[98:101]
	v_mfma_f32_16x16x32_bf16 v[86:89], v[184:187], v[230:233], v[86:89]
	v_mfma_f32_16x16x32_bf16 v[82:85], v[206:209], v[230:233], v[82:85]
	v_mfma_f32_16x16x32_bf16 v[70:73], v[184:187], v[244:247], v[70:73]
	v_mfma_f32_16x16x32_bf16 v[66:69], v[206:209], v[244:247], v[66:69]
	s_setprio 0
	s_barrier
; #define PG8_STAGE(bufoff, gbase, voff) do { _Pragma("unroll") for (int _i = 0; _i < 2; ++_i) \
;         __builtin_amdgcn_global_load_lds((const unsigned*)((const char*)(gbase) + (voff)[_i]), (PG8_LAS unsigned*)(lds + (bufoff) + ldsw + _i * 8192), 16, 0, 0); } while (0)
; #define PG8_BAR __builtin_amdgcn_s_barrier()
; template <class Epi, class Sched, bool ALIGN_EPI = false, bool SP2 = false>
; __device__ __forceinline__ void gemm_phase(PG8_LAS unsigned char* lds, const Gemm g, const Sched& S, const Epi& E) {
;     ...
;             PG8_WAIT_V(8); PG8_WAIT_L(0); PG8_BAR; PG8_MMA(0, 0, At, B0); PG8_MMA(0, 1, At, B1); PG8_BAR; PG8_SCHED;
;             PG8_LDA(At, 1, 1); PG8_STAGE(PG8_SB(1, 0), b3, voffB); PG8_STAGE(PG8_SB(1, 1), b3 + hstep, voffB); PG8_STAGE(PG8_SA(1, 0), a3, voffA);
;             PG8_WAIT_V(8); PG8_WAIT_L(0); PG8_BAR; PG8_MMA(1, 0, At, B0); PG8_MMA(1, 1, At, B1); PG8_BAR; PG8_SCHED;
;             } else {
;             PG8_LDB(B0, 0, 0); PG8_SCHED; PG8_LDA(At, 0, 0); PG8_STAGE(PG8_SA(1, 1), a1 + hstep, voffA);
;             PG8_WAIT_L(8); PG8_BAR; PG8_WAIT_L(0); PG8_MMA(0, 0, At, B0); PG8_BAR; PG8_SCHED;
;             PG8_LDB(B1, 0, 1); PG8_STAGE(PG8_SB(0, 0), b2, voffB);
;             PG8_BAR; PG8_WAIT_L(0); PG8_MMA(0, 1, At, B1); PG8_BAR;
;             PG8_LDA(At, 0, 1); PG8_STAGE(PG8_SA(0, 0), a2, voffA);
;             PG8_BAR; PG8_WAIT_L(0); PG8_MMA(1, 0, At, B0); PG8_BAR; PG8_SCHED;
;             PG8_STAGE(PG8_SB(0, 1), b2 + hstep, voffB);
;             PG8_WAIT_V(6); PG8_BAR; PG8_MMA(1, 1, At, B1); PG8_BAR;
;             PG8_LDB(B0, 1, 0); PG8_SCHED; PG8_LDA(At, 1, 0); PG8_STAGE(PG8_SA(0, 1), a2 + hstep, voffA);
;             PG8_WAIT_L(8); PG8_BAR; PG8_WAIT_L(0); PG8_MMA(0, 0, At, B0); PG8_BAR; PG8_SCHED;
;             PG8_LDB(B1, 1, 1); PG8_STAGE(PG8_SB(1, 0), b3, voffB);
;             PG8_BAR; PG8_WAIT_L(0); PG8_MMA(0, 1, At, B1); PG8_BAR;
;             PG8_LDA(At, 1, 1); PG8_STAGE(PG8_SA(1, 0), a3, voffA);
;             PG8_BAR; PG8_WAIT_L(0); PG8_MMA(1, 0, At, B0); PG8_BAR; PG8_SCHED;
;             PG8_STAGE(PG8_SB(1, 1), b3 + hstep, voffB);
;             PG8_WAIT_V(6); PG8_BAR; PG8_MMA(1, 1, At, B1); PG8_BAR;
;             }
;         }
;         if constexpr (ALIGN_EPI) { if (wr == 0) PG8_BAR; }
;         if constexpr (!Epi::AFTER_DRAIN) { E(acc, cur, wr, wc, fr, fq); S.done(cur); }
;         if (!has_next) break;
	s_add_i32 s24, s43, s28
	v_lshl_add_u64 v[164:165], v[238:239], 0, s[84:85]
	s_mov_b32 m0, s24
	ds_read_b128 v[210:213], v200 offset:49152
	ds_read_b128 v[214:217], v200 offset:50176
	ds_read_b128 v[218:221], v200 offset:51200
	ds_read_b128 v[222:225], v200 offset:52224
	ds_read_b128 v[226:229], v200 offset:53248
	ds_read_b128 v[230:233], v200 offset:54272
	ds_read_b128 v[234:237], v200 offset:55296
	ds_read_b128 v[244:247], v200 offset:56320
	global_load_lds_dwordx4 v[164:165], off
	s_add_i32 m0, s24, 0x2000
	s_add_u32 s6, s6, 0x10080
	v_lshl_add_u64 v[164:165], v[248:249], 0, s[84:85]
	s_addc_u32 s7, s7, 0
	s_add_i32 s24, s44, s28
	global_load_lds_dwordx4 v[164:165], off
	v_lshl_add_u64 v[164:165], s[6:7], 0, v[150:151]
	s_mov_b32 m0, s24
	v_lshl_add_u64 v[162:163], v[162:163], 0, s[84:85]
	global_load_lds_dwordx4 v[164:165], off
	v_lshl_add_u64 v[164:165], s[6:7], 0, v[146:147]
	s_add_i32 m0, s24, 0x2000
	s_nop 0
	global_load_lds_dwordx4 v[164:165], off
	v_lshl_add_u64 v[164:165], v[190:191], 0, s[84:85]
	s_mov_b32 m0, s35
	s_nop 0
	global_load_lds_dwordx4 v[164:165], off
	s_mov_b32 m0, s36
	s_nop 0
	global_load_lds_dwordx4 v[162:163], off
	s_waitcnt vmcnt(8)
	s_waitcnt lgkmcnt(0)
	s_barrier
	s_setprio 1
	s_waitcnt lgkmcnt(0)
	v_mfma_f32_16x16x32_bf16 v[62:65], v[130:133], v[210:213], v[62:65]
	v_mfma_f32_16x16x32_bf16 v[58:61], v[138:141], v[210:213], v[58:61]
	v_mfma_f32_16x16x32_bf16 v[46:49], v[130:133], v[218:221], v[46:49]
	v_mfma_f32_16x16x32_bf16 v[42:45], v[138:141], v[218:221], v[42:45]
	v_mfma_f32_16x16x32_bf16 v[30:33], v[130:133], v[226:229], v[30:33]
	v_mfma_f32_16x16x32_bf16 v[26:29], v[138:141], v[226:229], v[26:29]
	v_mfma_f32_16x16x32_bf16 v[14:17], v[130:133], v[234:237], v[14:17]
	v_mfma_f32_16x16x32_bf16 v[10:13], v[138:141], v[234:237], v[10:13]
	v_mfma_f32_16x16x32_bf16 v[62:65], v[134:137], v[214:217], v[62:65]
	v_mfma_f32_16x16x32_bf16 v[58:61], v[142:145], v[214:217], v[58:61]
	v_mfma_f32_16x16x32_bf16 v[46:49], v[134:137], v[222:225], v[46:49]
	v_mfma_f32_16x16x32_bf16 v[42:45], v[142:145], v[222:225], v[42:45]
	v_mfma_f32_16x16x32_bf16 v[30:33], v[134:137], v[230:233], v[30:33]
	v_mfma_f32_16x16x32_bf16 v[26:29], v[142:145], v[230:233], v[26:29]
	v_mfma_f32_16x16x32_bf16 v[14:17], v[134:137], v[244:247], v[14:17]
	v_mfma_f32_16x16x32_bf16 v[10:13], v[142:145], v[244:247], v[10:13]
	s_setprio 0
	s_setprio 1
	v_mfma_f32_16x16x32_bf16 v[54:57], v[180:183], v[210:213], v[54:57]
	v_mfma_f32_16x16x32_bf16 v[50:53], v[202:205], v[210:213], v[50:53]
	v_mfma_f32_16x16x32_bf16 v[38:41], v[180:183], v[218:221], v[38:41]
	v_mfma_f32_16x16x32_bf16 v[34:37], v[202:205], v[218:221], v[34:37]
	v_mfma_f32_16x16x32_bf16 v[22:25], v[180:183], v[226:229], v[22:25]
	v_mfma_f32_16x16x32_bf16 v[18:21], v[202:205], v[226:229], v[18:21]
	v_mfma_f32_16x16x32_bf16 v[6:9], v[180:183], v[234:237], v[6:9]
	v_mfma_f32_16x16x32_bf16 v[2:5], v[202:205], v[234:237], v[2:5]
	v_mfma_f32_16x16x32_bf16 v[54:57], v[184:187], v[214:217], v[54:57]
	v_mfma_f32_16x16x32_bf16 v[50:53], v[206:209], v[214:217], v[50:53]
	v_mfma_f32_16x16x32_bf16 v[38:41], v[184:187], v[222:225], v[38:41]
	v_mfma_f32_16x16x32_bf16 v[34:37], v[206:209], v[222:225], v[34:37]
	v_mfma_f32_16x16x32_bf16 v[22:25], v[184:187], v[230:233], v[22:25]
	v_mfma_f32_16x16x32_bf16 v[18:21], v[206:209], v[230:233], v[18:21]
	v_mfma_f32_16x16x32_bf16 v[6:9], v[184:187], v[244:247], v[6:9]
	v_mfma_f32_16x16x32_bf16 v[2:5], v[206:209], v[244:247], v[2:5]
	s_setprio 0
	s_barrier
	s_add_i32 s42, s42, 2
	s_add_u32 s2, s2, 0x100
	s_addc_u32 s3, s3, 0
	s_add_u32 s40, s40, 0x100
	s_addc_u32 s41, s41, 0
	s_cmp_gt_u32 s42, 13
	s_cbranch_scc0 .LBB0_155
	s_and_b64 vcc, exec, s[12:13]
	s_cbranch_vccz .LBB0_192
	s_barrier
	v_lshl_add_u32 v180, s33, 8, v155
	s_cmp_gt_i32 s64, 37
	s_mov_b64 s[2:3], -1
	s_cbranch_scc1 .LBB0_193

; DI float sigmoidf_(float v) { return __builtin_amdgcn_rcpf(1.0f + __expf(-v)); }
;     DI void operator()(const f32x4 (&acc)[2][2][4][2], const Unit& u, int wr, int wc, int fr, int fq) const {
;     ...
;                         if (sg) {
; #pragma unroll
;                             for (int i = 0; i < 4; ++i) { v0[i] = sigmoidf_(v0[i]); v1[i] = sigmoidf_(v1[i]); } }
.LBB0_159:
	s_cmp_lt_i32 s64, 26
	s_cbranch_scc1 .Lg1e_nosig
	v_mul_f32_e32 v126, 0xbfb8aa3b, v126
	v_mul_f32_e32 v127, 0xbfb8aa3b, v127
	v_mul_f32_e32 v128, 0xbfb8aa3b, v128
	v_mul_f32_e32 v129, 0xbfb8aa3b, v129
	v_mul_f32_e32 v122, 0xbfb8aa3b, v122
	v_mul_f32_e32 v123, 0xbfb8aa3b, v123
	v_mul_f32_e32 v124, 0xbfb8aa3b, v124
	v_mul_f32_e32 v125, 0xbfb8aa3b, v125
	v_exp_f32_e32 v126, v126
	v_exp_f32_e32 v127, v127
	v_exp_f32_e32 v128, v128
	v_exp_f32_e32 v129, v129
	v_exp_f32_e32 v122, v122
	v_exp_f32_e32 v123, v123
	v_exp_f32_e32 v124, v124
	v_exp_f32_e32 v125, v125
	v_add_f32_e32 v126, 1.0, v126
	v_add_f32_e32 v127, 1.0, v127
	v_add_f32_e32 v128, 1.0, v128
	v_add_f32_e32 v129, 1.0, v129
	v_add_f32_e32 v122, 1.0, v122
	v_add_f32_e32 v123, 1.0, v123
	v_add_f32_e32 v124, 1.0, v124
	v_add_f32_e32 v125, 1.0, v125
	v_rcp_f32_e32 v126, v126
	v_rcp_f32_e32 v127, v127
	v_rcp_f32_e32 v128, v128
	v_rcp_f32_e32 v129, v129
	v_rcp_f32_e32 v122, v122
	v_rcp_f32_e32 v123, v123
	v_rcp_f32_e32 v124, v124
	v_rcp_f32_e32 v125, v125
	v_mul_f32_e32 v118, 0xbfb8aa3b, v118
	v_mul_f32_e32 v119, 0xbfb8aa3b, v119
	v_mul_f32_e32 v120, 0xbfb8aa3b, v120
	v_mul_f32_e32 v121, 0xbfb8aa3b, v121
	v_mul_f32_e32 v114, 0xbfb8aa3b, v114
	v_mul_f32_e32 v115, 0xbfb8aa3b, v115
	v_mul_f32_e32 v116, 0xbfb8aa3b, v116
	v_mul_f32_e32 v117, 0xbfb8aa3b, v117
	v_exp_f32_e32 v118, v118
	v_exp_f32_e32 v119, v119
	v_exp_f32_e32 v120, v120
	v_exp_f32_e32 v121, v121
	v_exp_f32_e32 v114, v114
	v_exp_f32_e32 v115, v115
	v_exp_f32_e32 v116, v116
	v_exp_f32_e32 v117, v117
	v_add_f32_e32 v118, 1.0, v118
	v_add_f32_e32 v119, 1.0, v119
	v_add_f32_e32 v120, 1.0, v120
	v_add_f32_e32 v121, 1.0, v121
	v_add_f32_e32 v114, 1.0, v114
	v_add_f32_e32 v115, 1.0, v115
	v_add_f32_e32 v116, 1.0, v116
	v_add_f32_e32 v117, 1.0, v117
	v_rcp_f32_e32 v118, v118
	v_rcp_f32_e32 v119, v119
	v_rcp_f32_e32 v120, v120
	v_rcp_f32_e32 v121, v121
	v_rcp_f32_e32 v114, v114
	v_rcp_f32_e32 v115, v115
	v_rcp_f32_e32 v116, v116
	v_rcp_f32_e32 v117, v117
	v_mul_f32_e32 v110, 0xbfb8aa3b, v110
	v_mul_f32_e32 v111, 0xbfb8aa3b, v111
	v_mul_f32_e32 v112, 0xbfb8aa3b, v112
	v_mul_f32_e32 v113, 0xbfb8aa3b, v113
	v_mul_f32_e32 v106, 0xbfb8aa3b, v106
	v_mul_f32_e32 v107, 0xbfb8aa3b, v107
	v_mul_f32_e32 v108, 0xbfb8aa3b, v108
	v_mul_f32_e32 v109, 0xbfb8aa3b, v109
	v_exp_f32_e32 v110, v110
	v_exp_f32_e32 v111, v111
	v_exp_f32_e32 v112, v112
	v_exp_f32_e32 v113, v113
	v_exp_f32_e32 v106, v106
	v_exp_f32_e32 v107, v107
	v_exp_f32_e32 v108, v108
	v_exp_f32_e32 v109, v109
	v_add_f32_e32 v110, 1.0, v110
	v_add_f32_e32 v111, 1.0, v111
	v_add_f32_e32 v112, 1.0, v112
	v_add_f32_e32 v113, 1.0, v113
	v_add_f32_e32 v106, 1.0, v106
	v_add_f32_e32 v107, 1.0, v107
	v_add_f32_e32 v108, 1.0, v108
	v_add_f32_e32 v109, 1.0, v109
	v_rcp_f32_e32 v110, v110
	v_rcp_f32_e32 v111, v111
	v_rcp_f32_e32 v112, v112
	v_rcp_f32_e32 v113, v113
	v_rcp_f32_e32 v106, v106
	v_rcp_f32_e32 v107, v107
	v_rcp_f32_e32 v108, v108
	v_rcp_f32_e32 v109, v109
	v_mul_f32_e32 v102, 0xbfb8aa3b, v102
	v_mul_f32_e32 v103, 0xbfb8aa3b, v103
	v_mul_f32_e32 v104, 0xbfb8aa3b, v104
	v_mul_f32_e32 v105, 0xbfb8aa3b, v105
	v_mul_f32_e32 v98, 0xbfb8aa3b, v98
	v_mul_f32_e32 v99, 0xbfb8aa3b, v99
	v_mul_f32_e32 v100, 0xbfb8aa3b, v100
	v_mul_f32_e32 v101, 0xbfb8aa3b, v101
	v_exp_f32_e32 v102, v102
	v_exp_f32_e32 v103, v103
	v_exp_f32_e32 v104, v104
	v_exp_f32_e32 v105, v105
	v_exp_f32_e32 v98, v98
	v_exp_f32_e32 v99, v99
	v_exp_f32_e32 v100, v100
	v_exp_f32_e32 v101, v101
	v_add_f32_e32 v102, 1.0, v102
	v_add_f32_e32 v103, 1.0, v103
	v_add_f32_e32 v104, 1.0, v104
	v_add_f32_e32 v105, 1.0, v105
	v_add_f32_e32 v98, 1.0, v98
	v_add_f32_e32 v99, 1.0, v99
	v_add_f32_e32 v100, 1.0, v100
	v_add_f32_e32 v101, 1.0, v101
	v_rcp_f32_e32 v102, v102
	v_rcp_f32_e32 v103, v103
	v_rcp_f32_e32 v104, v104
	v_rcp_f32_e32 v105, v105
	v_rcp_f32_e32 v98, v98
	v_rcp_f32_e32 v99, v99
	v_rcp_f32_e32 v100, v100
	v_rcp_f32_e32 v101, v101
	v_mul_f32_e32 v94, 0xbfb8aa3b, v94
	v_mul_f32_e32 v95, 0xbfb8aa3b, v95
	v_mul_f32_e32 v96, 0xbfb8aa3b, v96
	v_mul_f32_e32 v97, 0xbfb8aa3b, v97
	v_mul_f32_e32 v90, 0xbfb8aa3b, v90
	v_mul_f32_e32 v91, 0xbfb8aa3b, v91
	v_mul_f32_e32 v92, 0xbfb8aa3b, v92
	v_mul_f32_e32 v93, 0xbfb8aa3b, v93
	v_exp_f32_e32 v94, v94
	v_exp_f32_e32 v95, v95
	v_exp_f32_e32 v96, v96
	v_exp_f32_e32 v97, v97
	v_exp_f32_e32 v90, v90
	v_exp_f32_e32 v91, v91
	v_exp_f32_e32 v92, v92
	v_exp_f32_e32 v93, v93
	v_add_f32_e32 v94, 1.0, v94
	v_add_f32_e32 v95, 1.0, v95
	v_add_f32_e32 v96, 1.0, v96
	v_add_f32_e32 v97, 1.0, v97
	v_add_f32_e32 v90, 1.0, v90
	v_add_f32_e32 v91, 1.0, v91
	v_add_f32_e32 v92, 1.0, v92
	v_add_f32_e32 v93, 1.0, v93
	v_rcp_f32_e32 v94, v94
	v_rcp_f32_e32 v95, v95
	v_rcp_f32_e32 v96, v96
	v_rcp_f32_e32 v97, v97
	v_rcp_f32_e32 v90, v90
	v_rcp_f32_e32 v91, v91
	v_rcp_f32_e32 v92, v92
	v_rcp_f32_e32 v93, v93
	v_mul_f32_e32 v86, 0xbfb8aa3b, v86
	v_mul_f32_e32 v87, 0xbfb8aa3b, v87
	v_mul_f32_e32 v88, 0xbfb8aa3b, v88
	v_mul_f32_e32 v89, 0xbfb8aa3b, v89
	v_mul_f32_e32 v82, 0xbfb8aa3b, v82
	v_mul_f32_e32 v83, 0xbfb8aa3b, v83
	v_mul_f32_e32 v84, 0xbfb8aa3b, v84
	v_mul_f32_e32 v85, 0xbfb8aa3b, v85
	v_exp_f32_e32 v86, v86
	v_exp_f32_e32 v87, v87
	v_exp_f32_e32 v88, v88
	v_exp_f32_e32 v89, v89
	v_exp_f32_e32 v82, v82
	v_exp_f32_e32 v83, v83
	v_exp_f32_e32 v84, v84
	v_exp_f32_e32 v85, v85
	v_add_f32_e32 v86, 1.0, v86
	v_add_f32_e32 v87, 1.0, v87
	v_add_f32_e32 v88, 1.0, v88
	v_add_f32_e32 v89, 1.0, v89
	v_add_f32_e32 v82, 1.0, v82
	v_add_f32_e32 v83, 1.0, v83
	v_add_f32_e32 v84, 1.0, v84
	v_add_f32_e32 v85, 1.0, v85
	v_rcp_f32_e32 v86, v86
	v_rcp_f32_e32 v87, v87
	v_rcp_f32_e32 v88, v88
	v_rcp_f32_e32 v89, v89
; DI float sigmoidf_(float v) { return __builtin_amdgcn_rcpf(1.0f + __expf(-v)); }
;     DI void operator()(const f32x4 (&acc)[2][2][4][2], const Unit& u, int wr, int wc, int fr, int fq) const {
;     ...
;                         if (sg) {
; #pragma unroll
;                             for (int i = 0; i < 4; ++i) { v0[i] = sigmoidf_(v0[i]); v1[i] = sigmoidf_(v1[i]); } }
	v_rcp_f32_e32 v82, v82
	v_rcp_f32_e32 v83, v83
	v_rcp_f32_e32 v84, v84
	v_rcp_f32_e32 v85, v85
	v_mul_f32_e32 v78, 0xbfb8aa3b, v78
	v_mul_f32_e32 v79, 0xbfb8aa3b, v79
	v_mul_f32_e32 v80, 0xbfb8aa3b, v80
	v_mul_f32_e32 v81, 0xbfb8aa3b, v81
	v_mul_f32_e32 v74, 0xbfb8aa3b, v74
	v_mul_f32_e32 v75, 0xbfb8aa3b, v75
	v_mul_f32_e32 v76, 0xbfb8aa3b, v76
	v_mul_f32_e32 v77, 0xbfb8aa3b, v77
	v_exp_f32_e32 v78, v78
	v_exp_f32_e32 v79, v79
	v_exp_f32_e32 v80, v80
	v_exp_f32_e32 v81, v81
	v_exp_f32_e32 v74, v74
	v_exp_f32_e32 v75, v75
	v_exp_f32_e32 v76, v76
	v_exp_f32_e32 v77, v77
	v_add_f32_e32 v78, 1.0, v78
	v_add_f32_e32 v79, 1.0, v79
	v_add_f32_e32 v80, 1.0, v80
	v_add_f32_e32 v81, 1.0, v81
	v_add_f32_e32 v74, 1.0, v74
	v_add_f32_e32 v75, 1.0, v75
	v_add_f32_e32 v76, 1.0, v76
	v_add_f32_e32 v77, 1.0, v77
	v_rcp_f32_e32 v78, v78
	v_rcp_f32_e32 v79, v79
	v_rcp_f32_e32 v80, v80
	v_rcp_f32_e32 v81, v81
	v_rcp_f32_e32 v74, v74
	v_rcp_f32_e32 v75, v75
	v_rcp_f32_e32 v76, v76
	v_rcp_f32_e32 v77, v77
	v_mul_f32_e32 v70, 0xbfb8aa3b, v70
	v_mul_f32_e32 v71, 0xbfb8aa3b, v71
	v_mul_f32_e32 v72, 0xbfb8aa3b, v72
	v_mul_f32_e32 v73, 0xbfb8aa3b, v73
	v_mul_f32_e32 v66, 0xbfb8aa3b, v66
	v_mul_f32_e32 v67, 0xbfb8aa3b, v67
	v_mul_f32_e32 v68, 0xbfb8aa3b, v68
	v_mul_f32_e32 v69, 0xbfb8aa3b, v69
	v_exp_f32_e32 v70, v70
	v_exp_f32_e32 v71, v71
	v_exp_f32_e32 v72, v72
	v_exp_f32_e32 v73, v73
	v_exp_f32_e32 v66, v66
	v_exp_f32_e32 v67, v67
	v_exp_f32_e32 v68, v68
	v_exp_f32_e32 v69, v69
	v_add_f32_e32 v70, 1.0, v70
	v_add_f32_e32 v71, 1.0, v71
	v_add_f32_e32 v72, 1.0, v72
	v_add_f32_e32 v73, 1.0, v73
	v_add_f32_e32 v66, 1.0, v66
	v_add_f32_e32 v67, 1.0, v67
	v_add_f32_e32 v68, 1.0, v68
	v_add_f32_e32 v69, 1.0, v69
	v_rcp_f32_e32 v70, v70
	v_rcp_f32_e32 v71, v71
	v_rcp_f32_e32 v72, v72
	v_rcp_f32_e32 v73, v73
	v_rcp_f32_e32 v66, v66
	v_rcp_f32_e32 v67, v67
	v_rcp_f32_e32 v68, v68
	v_rcp_f32_e32 v69, v69
	v_mul_f32_e32 v62, 0xbfb8aa3b, v62
	v_mul_f32_e32 v63, 0xbfb8aa3b, v63
	v_mul_f32_e32 v64, 0xbfb8aa3b, v64
	v_mul_f32_e32 v65, 0xbfb8aa3b, v65
	v_mul_f32_e32 v58, 0xbfb8aa3b, v58
	v_mul_f32_e32 v59, 0xbfb8aa3b, v59
	v_mul_f32_e32 v60, 0xbfb8aa3b, v60
	v_mul_f32_e32 v61, 0xbfb8aa3b, v61
	v_exp_f32_e32 v62, v62
	v_exp_f32_e32 v63, v63
	v_exp_f32_e32 v64, v64
	v_exp_f32_e32 v65, v65
	v_exp_f32_e32 v58, v58
	v_exp_f32_e32 v59, v59
	v_exp_f32_e32 v60, v60
	v_exp_f32_e32 v61, v61
	v_add_f32_e32 v62, 1.0, v62
	v_add_f32_e32 v63, 1.0, v63
	v_add_f32_e32 v64, 1.0, v64
	v_add_f32_e32 v65, 1.0, v65
	v_add_f32_e32 v58, 1.0, v58
	v_add_f32_e32 v59, 1.0, v59
	v_add_f32_e32 v60, 1.0, v60
	v_add_f32_e32 v61, 1.0, v61
	v_rcp_f32_e32 v62, v62
	v_rcp_f32_e32 v63, v63
	v_rcp_f32_e32 v64, v64
	v_rcp_f32_e32 v65, v65
	v_rcp_f32_e32 v58, v58
	v_rcp_f32_e32 v59, v59
	v_rcp_f32_e32 v60, v60
	v_rcp_f32_e32 v61, v61
	v_mul_f32_e32 v54, 0xbfb8aa3b, v54
	v_mul_f32_e32 v55, 0xbfb8aa3b, v55
	v_mul_f32_e32 v56, 0xbfb8aa3b, v56
	v_mul_f32_e32 v57, 0xbfb8aa3b, v57
	v_mul_f32_e32 v50, 0xbfb8aa3b, v50
	v_mul_f32_e32 v51, 0xbfb8aa3b, v51
	v_mul_f32_e32 v52, 0xbfb8aa3b, v52
	v_mul_f32_e32 v53, 0xbfb8aa3b, v53
	v_exp_f32_e32 v54, v54
	v_exp_f32_e32 v55, v55
	v_exp_f32_e32 v56, v56
	v_exp_f32_e32 v57, v57
	v_exp_f32_e32 v50, v50
	v_exp_f32_e32 v51, v51
	v_exp_f32_e32 v52, v52
	v_exp_f32_e32 v53, v53
	v_add_f32_e32 v54, 1.0, v54
	v_add_f32_e32 v55, 1.0, v55
	v_add_f32_e32 v56, 1.0, v56
	v_add_f32_e32 v57, 1.0, v57
	v_add_f32_e32 v50, 1.0, v50
	v_add_f32_e32 v51, 1.0, v51
	v_add_f32_e32 v52, 1.0, v52
	v_add_f32_e32 v53, 1.0, v53
	v_rcp_f32_e32 v54, v54
	v_rcp_f32_e32 v55, v55
	v_rcp_f32_e32 v56, v56
	v_rcp_f32_e32 v57, v57
	v_rcp_f32_e32 v50, v50
	v_rcp_f32_e32 v51, v51
	v_rcp_f32_e32 v52, v52
	v_rcp_f32_e32 v53, v53
	v_mul_f32_e32 v46, 0xbfb8aa3b, v46
	v_mul_f32_e32 v47, 0xbfb8aa3b, v47
	v_mul_f32_e32 v48, 0xbfb8aa3b, v48
	v_mul_f32_e32 v49, 0xbfb8aa3b, v49
	v_mul_f32_e32 v42, 0xbfb8aa3b, v42
	v_mul_f32_e32 v43, 0xbfb8aa3b, v43
	v_mul_f32_e32 v44, 0xbfb8aa3b, v44
	v_mul_f32_e32 v45, 0xbfb8aa3b, v45
	v_exp_f32_e32 v46, v46
	v_exp_f32_e32 v47, v47
	v_exp_f32_e32 v48, v48
	v_exp_f32_e32 v49, v49
	v_exp_f32_e32 v42, v42
	v_exp_f32_e32 v43, v43
	v_exp_f32_e32 v44, v44
	v_exp_f32_e32 v45, v45
	v_add_f32_e32 v46, 1.0, v46
	v_add_f32_e32 v47, 1.0, v47
	v_add_f32_e32 v48, 1.0, v48
	v_add_f32_e32 v49, 1.0, v49
	v_add_f32_e32 v42, 1.0, v42
	v_add_f32_e32 v43, 1.0, v43
	v_add_f32_e32 v44, 1.0, v44
	v_add_f32_e32 v45, 1.0, v45
	v_rcp_f32_e32 v46, v46
	v_rcp_f32_e32 v47, v47
	v_rcp_f32_e32 v48, v48
	v_rcp_f32_e32 v49, v49
	v_rcp_f32_e32 v42, v42
	v_rcp_f32_e32 v43, v43
	v_rcp_f32_e32 v44, v44
	v_rcp_f32_e32 v45, v45
	v_mul_f32_e32 v38, 0xbfb8aa3b, v38
	v_mul_f32_e32 v39, 0xbfb8aa3b, v39
	v_mul_f32_e32 v40, 0xbfb8aa3b, v40
	v_mul_f32_e32 v41, 0xbfb8aa3b, v41
	v_mul_f32_e32 v34, 0xbfb8aa3b, v34
	v_mul_f32_e32 v35, 0xbfb8aa3b, v35
	v_mul_f32_e32 v36, 0xbfb8aa3b, v36
	v_mul_f32_e32 v37, 0xbfb8aa3b, v37
	v_exp_f32_e32 v38, v38
	v_exp_f32_e32 v39, v39
	v_exp_f32_e32 v40, v40
	v_exp_f32_e32 v41, v41
	v_exp_f32_e32 v34, v34
	v_exp_f32_e32 v35, v35
	v_exp_f32_e32 v36, v36
	v_exp_f32_e32 v37, v37
	v_add_f32_e32 v38, 1.0, v38
	v_add_f32_e32 v39, 1.0, v39
	v_add_f32_e32 v40, 1.0, v40
	v_add_f32_e32 v41, 1.0, v41
	v_add_f32_e32 v34, 1.0, v34
	v_add_f32_e32 v35, 1.0, v35
	v_add_f32_e32 v36, 1.0, v36
	v_add_f32_e32 v37, 1.0, v37
	v_rcp_f32_e32 v38, v38
	v_rcp_f32_e32 v39, v39
	v_rcp_f32_e32 v40, v40
	v_rcp_f32_e32 v41, v41
	v_rcp_f32_e32 v34, v34
	v_rcp_f32_e32 v35, v35
	v_rcp_f32_e32 v36, v36
	v_rcp_f32_e32 v37, v37
	v_mul_f32_e32 v30, 0xbfb8aa3b, v30
	v_mul_f32_e32 v31, 0xbfb8aa3b, v31
	v_mul_f32_e32 v32, 0xbfb8aa3b, v32
; DI unsigned pk2(float lo, float hi) { return pg8::cvt_pk_bf16(lo, hi); }
; DI float sigmoidf_(float v) { return __builtin_amdgcn_rcpf(1.0f + __expf(-v)); }
;     DI void operator()(const f32x4 (&acc)[2][2][4][2], const Unit& u, int wr, int wc, int fr, int fq) const {
;     ...
;                         if (sg) {
; #pragma unroll
;                             for (int i = 0; i < 4; ++i) { v0[i] = sigmoidf_(v0[i]); v1[i] = sigmoidf_(v1[i]); } }
;                         v4u w; w.x = pk2(v0[0], v0[1]); w.y = pk2(v0[2], v0[3]); w.z = pk2(v1[0], v1[1]); w.w = pk2(v1[2], v1[3]);
;                         __builtin_nontemporal_store(w, (v4u*)(rowp + bj * 128)); } }
	v_mul_f32_e32 v33, 0xbfb8aa3b, v33
	v_mul_f32_e32 v26, 0xbfb8aa3b, v26
	v_mul_f32_e32 v27, 0xbfb8aa3b, v27
	v_mul_f32_e32 v28, 0xbfb8aa3b, v28
	v_mul_f32_e32 v29, 0xbfb8aa3b, v29
	v_exp_f32_e32 v30, v30
	v_exp_f32_e32 v31, v31
	v_exp_f32_e32 v32, v32
	v_exp_f32_e32 v33, v33
	v_exp_f32_e32 v26, v26
	v_exp_f32_e32 v27, v27
	v_exp_f32_e32 v28, v28
	v_exp_f32_e32 v29, v29
	v_add_f32_e32 v30, 1.0, v30
	v_add_f32_e32 v31, 1.0, v31
	v_add_f32_e32 v32, 1.0, v32
	v_add_f32_e32 v33, 1.0, v33
	v_add_f32_e32 v26, 1.0, v26
	v_add_f32_e32 v27, 1.0, v27
	v_add_f32_e32 v28, 1.0, v28
	v_add_f32_e32 v29, 1.0, v29
	v_rcp_f32_e32 v30, v30
	v_rcp_f32_e32 v31, v31
	v_rcp_f32_e32 v32, v32
	v_rcp_f32_e32 v33, v33
	v_rcp_f32_e32 v26, v26
	v_rcp_f32_e32 v27, v27
	v_rcp_f32_e32 v28, v28
	v_rcp_f32_e32 v29, v29
	v_mul_f32_e32 v22, 0xbfb8aa3b, v22
	v_mul_f32_e32 v23, 0xbfb8aa3b, v23
	v_mul_f32_e32 v24, 0xbfb8aa3b, v24
	v_mul_f32_e32 v25, 0xbfb8aa3b, v25
	v_mul_f32_e32 v18, 0xbfb8aa3b, v18
	v_mul_f32_e32 v19, 0xbfb8aa3b, v19
	v_mul_f32_e32 v20, 0xbfb8aa3b, v20
	v_mul_f32_e32 v21, 0xbfb8aa3b, v21
	v_exp_f32_e32 v22, v22
	v_exp_f32_e32 v23, v23
	v_exp_f32_e32 v24, v24
	v_exp_f32_e32 v25, v25
	v_exp_f32_e32 v18, v18
	v_exp_f32_e32 v19, v19
	v_exp_f32_e32 v20, v20
	v_exp_f32_e32 v21, v21
	v_add_f32_e32 v22, 1.0, v22
	v_add_f32_e32 v23, 1.0, v23
	v_add_f32_e32 v24, 1.0, v24
	v_add_f32_e32 v25, 1.0, v25
	v_add_f32_e32 v18, 1.0, v18
	v_add_f32_e32 v19, 1.0, v19
	v_add_f32_e32 v20, 1.0, v20
	v_add_f32_e32 v21, 1.0, v21
	v_rcp_f32_e32 v22, v22
	v_rcp_f32_e32 v23, v23
	v_rcp_f32_e32 v24, v24
	v_rcp_f32_e32 v25, v25
	v_rcp_f32_e32 v18, v18
	v_rcp_f32_e32 v19, v19
	v_rcp_f32_e32 v20, v20
	v_rcp_f32_e32 v21, v21
	v_mul_f32_e32 v14, 0xbfb8aa3b, v14
	v_mul_f32_e32 v15, 0xbfb8aa3b, v15
	v_mul_f32_e32 v16, 0xbfb8aa3b, v16
	v_mul_f32_e32 v17, 0xbfb8aa3b, v17
	v_mul_f32_e32 v10, 0xbfb8aa3b, v10
	v_mul_f32_e32 v11, 0xbfb8aa3b, v11
	v_mul_f32_e32 v12, 0xbfb8aa3b, v12
	v_mul_f32_e32 v13, 0xbfb8aa3b, v13
	v_exp_f32_e32 v14, v14
	v_exp_f32_e32 v15, v15
	v_exp_f32_e32 v16, v16
	v_exp_f32_e32 v17, v17
	v_exp_f32_e32 v10, v10
	v_exp_f32_e32 v11, v11
	v_exp_f32_e32 v12, v12
	v_exp_f32_e32 v13, v13
	v_add_f32_e32 v14, 1.0, v14
	v_add_f32_e32 v15, 1.0, v15
	v_add_f32_e32 v16, 1.0, v16
	v_add_f32_e32 v17, 1.0, v17
	v_add_f32_e32 v10, 1.0, v10
	v_add_f32_e32 v11, 1.0, v11
	v_add_f32_e32 v12, 1.0, v12
	v_add_f32_e32 v13, 1.0, v13
	v_rcp_f32_e32 v14, v14
	v_rcp_f32_e32 v15, v15
	v_rcp_f32_e32 v16, v16
	v_rcp_f32_e32 v17, v17
	v_rcp_f32_e32 v10, v10
	v_rcp_f32_e32 v11, v11
	v_rcp_f32_e32 v12, v12
	v_rcp_f32_e32 v13, v13
	v_mul_f32_e32 v6, 0xbfb8aa3b, v6
	v_mul_f32_e32 v7, 0xbfb8aa3b, v7
	v_mul_f32_e32 v8, 0xbfb8aa3b, v8
	v_mul_f32_e32 v9, 0xbfb8aa3b, v9
	v_mul_f32_e32 v2, 0xbfb8aa3b, v2
	v_mul_f32_e32 v3, 0xbfb8aa3b, v3
	v_mul_f32_e32 v4, 0xbfb8aa3b, v4
	v_mul_f32_e32 v5, 0xbfb8aa3b, v5
	v_exp_f32_e32 v6, v6
	v_exp_f32_e32 v7, v7
	v_exp_f32_e32 v8, v8
	v_exp_f32_e32 v9, v9
	v_exp_f32_e32 v2, v2
	v_exp_f32_e32 v3, v3
	v_exp_f32_e32 v4, v4
	v_exp_f32_e32 v5, v5
	v_add_f32_e32 v6, 1.0, v6
	v_add_f32_e32 v7, 1.0, v7
	v_add_f32_e32 v8, 1.0, v8
	v_add_f32_e32 v9, 1.0, v9
	v_add_f32_e32 v2, 1.0, v2
	v_add_f32_e32 v3, 1.0, v3
	v_add_f32_e32 v4, 1.0, v4
	v_add_f32_e32 v5, 1.0, v5
	v_rcp_f32_e32 v6, v6
	v_rcp_f32_e32 v7, v7
	v_rcp_f32_e32 v8, v8
	v_rcp_f32_e32 v9, v9
	v_rcp_f32_e32 v2, v2
	v_rcp_f32_e32 v3, v3
	v_rcp_f32_e32 v4, v4
	v_rcp_f32_e32 v5, v5
.Lg1e_nosig:
	s_ashr_i32 s65, s64, 31
	s_lshl_b64 s[2:3], s[64:65], 24
	s_add_u32 s2, s86, s2
	s_addc_u32 s3, s87, s3
	v_and_b32_e32 v202, 0xfffffff7, v180
	v_ashrrev_i32_e32 v203, 31, v202
	v_lshlrev_b64 v[202:203], 9, v[202:203]
	v_lshl_add_u64 v[202:203], s[2:3], 0, v[202:203]
	v_lshrrev_b32_e32 v204, 5, v154
	v_lshlrev_b32_e32 v204, 7, v204
	v_bfe_u32 v205, v154, 3, 2
	v_lshl_or_b32 v204, v205, 4, v204
	v_bfe_u32 v205, v180, 3, 1
	v_lshl_or_b32 v204, v205, 6, v204
	v_add_u32_e32 v204, 0x1000, v204
	v_mov_b32_e32 v205, 0
	v_lshl_add_u64 v[202:203], v[202:203], 0, v[204:205]
	v_cvt_pk_bf16_f32 v208, v126, v127
	v_cvt_pk_bf16_f32 v209, v128, v129
	v_cvt_pk_bf16_f32 v210, v122, v123
	v_cvt_pk_bf16_f32 v211, v124, v125
	v_cvt_pk_bf16_f32 v212, v118, v119
	v_cvt_pk_bf16_f32 v213, v120, v121
	v_cvt_pk_bf16_f32 v214, v114, v115
	v_cvt_pk_bf16_f32 v215, v116, v117
	v_mov_b32_e32 v216, v212
	v_mov_b32_e32 v217, v213
	v_mov_b32_e32 v218, v214
	v_mov_b32_e32 v219, v215
	v_mov_b32_dpp v212, v208 row_shl:8 row_mask:0xf bank_mask:0x3
	v_mov_b32_dpp v213, v209 row_shl:8 row_mask:0xf bank_mask:0x3
	v_mov_b32_dpp v214, v210 row_shl:8 row_mask:0xf bank_mask:0x3
	v_mov_b32_dpp v215, v211 row_shl:8 row_mask:0xf bank_mask:0x3
	v_mov_b32_dpp v208, v216 row_shr:8 row_mask:0xf bank_mask:0xc
	v_mov_b32_dpp v209, v217 row_shr:8 row_mask:0xf bank_mask:0xc
	v_mov_b32_dpp v210, v218 row_shr:8 row_mask:0xf bank_mask:0xc
	v_mov_b32_dpp v211, v219 row_shr:8 row_mask:0xf bank_mask:0xc
	global_store_dwordx4 v[202:203], v[208:211], off offset:-4096 nt
	global_store_dwordx4 v[202:203], v[212:215], off nt
	v_cvt_pk_bf16_f32 v224, v110, v111
	v_cvt_pk_bf16_f32 v225, v112, v113
	v_cvt_pk_bf16_f32 v226, v106, v107
	v_cvt_pk_bf16_f32 v227, v108, v109
	v_cvt_pk_bf16_f32 v228, v102, v103
	v_cvt_pk_bf16_f32 v229, v104, v105
	v_cvt_pk_bf16_f32 v230, v98, v99
	v_cvt_pk_bf16_f32 v231, v100, v101
	v_mov_b32_e32 v232, v228
	v_mov_b32_e32 v233, v229
	v_mov_b32_e32 v234, v230
	v_mov_b32_e32 v235, v231
	v_mov_b32_dpp v228, v224 row_shl:8 row_mask:0xf bank_mask:0x3
	v_mov_b32_dpp v229, v225 row_shl:8 row_mask:0xf bank_mask:0x3
	v_mov_b32_dpp v230, v226 row_shl:8 row_mask:0xf bank_mask:0x3
; DI size_t pidx(size_t row, int col) { return (size_t)(col >> 8) * ((size_t)TH * 256) + row * 256 + (size_t)(col & 255); }
; DI unsigned pk2(float lo, float hi) { return pg8::cvt_pk_bf16(lo, hi); }
; DI float sigmoidf_(float v) { return __builtin_amdgcn_rcpf(1.0f + __expf(-v)); }
;     DI void operator()(const f32x4 (&acc)[2][2][4][2], const Unit& u, int wr, int wc, int fr, int fq) const {
;     ...
;             for (int ai = 0; ai < 2; ++ai)
; #pragma unroll
;                 for (int m = 0; m < 4; ++m) { bf16* rowp = P + pidx((size_t)(row0 + ai * 128 + m * 16), col0);
; #pragma unroll
;                     for (int bj = 0; bj < 2; ++bj) { f32x4 v0 = acc[ai][bj][m][0], v1 = acc[ai][bj][m][1];
;                         if (sg) {
; #pragma unroll
;                             for (int i = 0; i < 4; ++i) { v0[i] = sigmoidf_(v0[i]); v1[i] = sigmoidf_(v1[i]); } }
;                         v4u w; w.x = pk2(v0[0], v0[1]); w.y = pk2(v0[2], v0[3]); w.z = pk2(v1[0], v1[1]); w.w = pk2(v1[2], v1[3]);
;                         __builtin_nontemporal_store(w, (v4u*)(rowp + bj * 128)); } }
	v_mov_b32_dpp v231, v227 row_shl:8 row_mask:0xf bank_mask:0x3
	v_mov_b32_dpp v224, v232 row_shr:8 row_mask:0xf bank_mask:0xc
	v_mov_b32_dpp v225, v233 row_shr:8 row_mask:0xf bank_mask:0xc
	v_mov_b32_dpp v226, v234 row_shr:8 row_mask:0xf bank_mask:0xc
	v_mov_b32_dpp v227, v235 row_shr:8 row_mask:0xf bank_mask:0xc
	s_mov_b64 s[98:99], 0x2000
	v_lshl_add_u64 v[206:207], v[202:203], 0, s[98:99]
	global_store_dwordx4 v[206:207], v[224:227], off offset:-4096 nt
	global_store_dwordx4 v[206:207], v[228:231], off nt
	v_cvt_pk_bf16_f32 v208, v94, v95
	v_cvt_pk_bf16_f32 v209, v96, v97
	v_cvt_pk_bf16_f32 v210, v90, v91
	v_cvt_pk_bf16_f32 v211, v92, v93
	v_cvt_pk_bf16_f32 v212, v86, v87
	v_cvt_pk_bf16_f32 v213, v88, v89
	v_cvt_pk_bf16_f32 v214, v82, v83
	v_cvt_pk_bf16_f32 v215, v84, v85
	v_mov_b32_e32 v216, v212
	v_mov_b32_e32 v217, v213
	v_mov_b32_e32 v218, v214
	v_mov_b32_e32 v219, v215
	v_mov_b32_dpp v212, v208 row_shl:8 row_mask:0xf bank_mask:0x3
	v_mov_b32_dpp v213, v209 row_shl:8 row_mask:0xf bank_mask:0x3
	v_mov_b32_dpp v214, v210 row_shl:8 row_mask:0xf bank_mask:0x3
	v_mov_b32_dpp v215, v211 row_shl:8 row_mask:0xf bank_mask:0x3
	v_mov_b32_dpp v208, v216 row_shr:8 row_mask:0xf bank_mask:0xc
	v_mov_b32_dpp v209, v217 row_shr:8 row_mask:0xf bank_mask:0xc
	v_mov_b32_dpp v210, v218 row_shr:8 row_mask:0xf bank_mask:0xc
	v_mov_b32_dpp v211, v219 row_shr:8 row_mask:0xf bank_mask:0xc
	s_mov_b64 s[98:99], 0x4000
	v_lshl_add_u64 v[206:207], v[202:203], 0, s[98:99]
	global_store_dwordx4 v[206:207], v[208:211], off offset:-4096 nt
	global_store_dwordx4 v[206:207], v[212:215], off nt
	v_cvt_pk_bf16_f32 v224, v78, v79
	v_cvt_pk_bf16_f32 v225, v80, v81
	v_cvt_pk_bf16_f32 v226, v74, v75
	v_cvt_pk_bf16_f32 v227, v76, v77
	v_cvt_pk_bf16_f32 v228, v70, v71
	v_cvt_pk_bf16_f32 v229, v72, v73
	v_cvt_pk_bf16_f32 v230, v66, v67
	v_cvt_pk_bf16_f32 v231, v68, v69
	v_mov_b32_e32 v232, v228
	v_mov_b32_e32 v233, v229
	v_mov_b32_e32 v234, v230
	v_mov_b32_e32 v235, v231
	v_mov_b32_dpp v228, v224 row_shl:8 row_mask:0xf bank_mask:0x3
	v_mov_b32_dpp v229, v225 row_shl:8 row_mask:0xf bank_mask:0x3
	v_mov_b32_dpp v230, v226 row_shl:8 row_mask:0xf bank_mask:0x3
	v_mov_b32_dpp v231, v227 row_shl:8 row_mask:0xf bank_mask:0x3
	v_mov_b32_dpp v224, v232 row_shr:8 row_mask:0xf bank_mask:0xc
	v_mov_b32_dpp v225, v233 row_shr:8 row_mask:0xf bank_mask:0xc
	v_mov_b32_dpp v226, v234 row_shr:8 row_mask:0xf bank_mask:0xc
	v_mov_b32_dpp v227, v235 row_shr:8 row_mask:0xf bank_mask:0xc
	s_mov_b64 s[98:99], 0x6000
	v_lshl_add_u64 v[206:207], v[202:203], 0, s[98:99]
	global_store_dwordx4 v[206:207], v[224:227], off offset:-4096 nt
	global_store_dwordx4 v[206:207], v[228:231], off nt
	v_cvt_pk_bf16_f32 v208, v62, v63
	v_cvt_pk_bf16_f32 v209, v64, v65
	v_cvt_pk_bf16_f32 v210, v58, v59
	v_cvt_pk_bf16_f32 v211, v60, v61
	v_cvt_pk_bf16_f32 v212, v54, v55
	v_cvt_pk_bf16_f32 v213, v56, v57
	v_cvt_pk_bf16_f32 v214, v50, v51
	v_cvt_pk_bf16_f32 v215, v52, v53
	v_mov_b32_e32 v216, v212
	v_mov_b32_e32 v217, v213
	v_mov_b32_e32 v218, v214
	v_mov_b32_e32 v219, v215
	v_mov_b32_dpp v212, v208 row_shl:8 row_mask:0xf bank_mask:0x3
	v_mov_b32_dpp v213, v209 row_shl:8 row_mask:0xf bank_mask:0x3
	v_mov_b32_dpp v214, v210 row_shl:8 row_mask:0xf bank_mask:0x3
	v_mov_b32_dpp v215, v211 row_shl:8 row_mask:0xf bank_mask:0x3
	v_mov_b32_dpp v208, v216 row_shr:8 row_mask:0xf bank_mask:0xc
	v_mov_b32_dpp v209, v217 row_shr:8 row_mask:0xf bank_mask:0xc
	v_mov_b32_dpp v210, v218 row_shr:8 row_mask:0xf bank_mask:0xc
	v_mov_b32_dpp v211, v219 row_shr:8 row_mask:0xf bank_mask:0xc
; DI size_t pidx(size_t row, int col) { return (size_t)(col >> 8) * ((size_t)TH * 256) + row * 256 + (size_t)(col & 255); }
; DI unsigned pk2(float lo, float hi) { return pg8::cvt_pk_bf16(lo, hi); }
; DI float sigmoidf_(float v) { return __builtin_amdgcn_rcpf(1.0f + __expf(-v)); }
;     DI void operator()(const f32x4 (&acc)[2][2][4][2], const Unit& u, int wr, int wc, int fr, int fq) const {
;     ...
;             for (int ai = 0; ai < 2; ++ai)
; #pragma unroll
;                 for (int m = 0; m < 4; ++m) { bf16* rowp = P + pidx((size_t)(row0 + ai * 128 + m * 16), col0);
; #pragma unroll
;                     for (int bj = 0; bj < 2; ++bj) { f32x4 v0 = acc[ai][bj][m][0], v1 = acc[ai][bj][m][1];
;                         if (sg) {
; #pragma unroll
;                             for (int i = 0; i < 4; ++i) { v0[i] = sigmoidf_(v0[i]); v1[i] = sigmoidf_(v1[i]); } }
;                         v4u w; w.x = pk2(v0[0], v0[1]); w.y = pk2(v0[2], v0[3]); w.z = pk2(v1[0], v1[1]); w.w = pk2(v1[2], v1[3]);
;                         __builtin_nontemporal_store(w, (v4u*)(rowp + bj * 128)); } }
	s_mov_b64 s[98:99], 0x10000
	v_lshl_add_u64 v[206:207], v[202:203], 0, s[98:99]
	global_store_dwordx4 v[206:207], v[208:211], off offset:-4096 nt
	global_store_dwordx4 v[206:207], v[212:215], off nt
	v_cvt_pk_bf16_f32 v224, v46, v47
	v_cvt_pk_bf16_f32 v225, v48, v49
	v_cvt_pk_bf16_f32 v226, v42, v43
	v_cvt_pk_bf16_f32 v227, v44, v45
	v_cvt_pk_bf16_f32 v228, v38, v39
	v_cvt_pk_bf16_f32 v229, v40, v41
	v_cvt_pk_bf16_f32 v230, v34, v35
	v_cvt_pk_bf16_f32 v231, v36, v37
	v_mov_b32_e32 v232, v228
	v_mov_b32_e32 v233, v229
	v_mov_b32_e32 v234, v230
	v_mov_b32_e32 v235, v231
	v_mov_b32_dpp v228, v224 row_shl:8 row_mask:0xf bank_mask:0x3
	v_mov_b32_dpp v229, v225 row_shl:8 row_mask:0xf bank_mask:0x3
	v_mov_b32_dpp v230, v226 row_shl:8 row_mask:0xf bank_mask:0x3
	v_mov_b32_dpp v231, v227 row_shl:8 row_mask:0xf bank_mask:0x3
	v_mov_b32_dpp v224, v232 row_shr:8 row_mask:0xf bank_mask:0xc
	v_mov_b32_dpp v225, v233 row_shr:8 row_mask:0xf bank_mask:0xc
	v_mov_b32_dpp v226, v234 row_shr:8 row_mask:0xf bank_mask:0xc
	v_mov_b32_dpp v227, v235 row_shr:8 row_mask:0xf bank_mask:0xc
	s_mov_b64 s[98:99], 0x12000
	v_lshl_add_u64 v[206:207], v[202:203], 0, s[98:99]
	global_store_dwordx4 v[206:207], v[224:227], off offset:-4096 nt
	global_store_dwordx4 v[206:207], v[228:231], off nt
	v_cvt_pk_bf16_f32 v208, v30, v31
	v_cvt_pk_bf16_f32 v209, v32, v33
	v_cvt_pk_bf16_f32 v210, v26, v27
	v_cvt_pk_bf16_f32 v211, v28, v29
	v_cvt_pk_bf16_f32 v212, v22, v23
	v_cvt_pk_bf16_f32 v213, v24, v25
	v_cvt_pk_bf16_f32 v214, v18, v19
	v_cvt_pk_bf16_f32 v215, v20, v21
	v_mov_b32_e32 v216, v212
	v_mov_b32_e32 v217, v213
	v_mov_b32_e32 v218, v214
	v_mov_b32_e32 v219, v215
	v_mov_b32_dpp v212, v208 row_shl:8 row_mask:0xf bank_mask:0x3
	v_mov_b32_dpp v213, v209 row_shl:8 row_mask:0xf bank_mask:0x3
	v_mov_b32_dpp v214, v210 row_shl:8 row_mask:0xf bank_mask:0x3
	v_mov_b32_dpp v215, v211 row_shl:8 row_mask:0xf bank_mask:0x3
	v_mov_b32_dpp v208, v216 row_shr:8 row_mask:0xf bank_mask:0xc
	v_mov_b32_dpp v209, v217 row_shr:8 row_mask:0xf bank_mask:0xc
	v_mov_b32_dpp v210, v218 row_shr:8 row_mask:0xf bank_mask:0xc
	v_mov_b32_dpp v211, v219 row_shr:8 row_mask:0xf bank_mask:0xc
	s_mov_b64 s[98:99], 0x14000
	v_lshl_add_u64 v[206:207], v[202:203], 0, s[98:99]
	global_store_dwordx4 v[206:207], v[208:211], off offset:-4096 nt
	global_store_dwordx4 v[206:207], v[212:215], off nt
	v_cvt_pk_bf16_f32 v224, v14, v15
	v_cvt_pk_bf16_f32 v225, v16, v17
	v_cvt_pk_bf16_f32 v226, v10, v11
	v_cvt_pk_bf16_f32 v227, v12, v13
	v_cvt_pk_bf16_f32 v228, v6, v7
	v_cvt_pk_bf16_f32 v229, v8, v9
	v_cvt_pk_bf16_f32 v230, v2, v3
	v_cvt_pk_bf16_f32 v231, v4, v5
	v_mov_b32_e32 v232, v228
	v_mov_b32_e32 v233, v229
	v_mov_b32_e32 v234, v230
	v_mov_b32_e32 v235, v231
	v_mov_b32_dpp v228, v224 row_shl:8 row_mask:0xf bank_mask:0x3
	v_mov_b32_dpp v229, v225 row_shl:8 row_mask:0xf bank_mask:0x3
	v_mov_b32_dpp v230, v226 row_shl:8 row_mask:0xf bank_mask:0x3
	v_mov_b32_dpp v231, v227 row_shl:8 row_mask:0xf bank_mask:0x3
	v_mov_b32_dpp v224, v232 row_shr:8 row_mask:0xf bank_mask:0xc
	v_mov_b32_dpp v225, v233 row_shr:8 row_mask:0xf bank_mask:0xc
	v_mov_b32_dpp v226, v234 row_shr:8 row_mask:0xf bank_mask:0xc
	v_mov_b32_dpp v227, v235 row_shr:8 row_mask:0xf bank_mask:0xc
	s_mov_b64 s[98:99], 0x16000
	v_lshl_add_u64 v[206:207], v[202:203], 0, s[98:99]
	global_store_dwordx4 v[206:207], v[224:227], off offset:-4096 nt
	global_store_dwordx4 v[206:207], v[228:231], off nt
	s_andn2_b64 vcc, exec, s[4:5]
	s_mov_b64 s[2:3], -1
	s_cbranch_vccnz .LBB0_151
	s_branch .LBB0_213
